# rmsnorm row loops issue all 4 row loads up front; phase-2 epilogue restores s34 constant
# speedup vs baseline: 1.1415x; 1.0044x over previous
.LBB0_286:
	v_ashrrev_i32_e32 v17, 31, v16
	v_lshlrev_b64 v[28:29], 12, v[16:17]
	v_lshl_add_u64 v[40:41], v[18:19], 0, v[28:29]
	v_lshlrev_b64 v[28:29], 11, v[16:17]
	v_lshl_add_u64 v[44:45], v[20:21], 0, v[28:29]
	global_load_dwordx4 v[28:31], v[40:41], off
	global_load_dwordx4 v[32:35], v[40:41], off offset:1024
	global_load_dwordx4 v[56:59], v[40:41], off offset:2048
	global_load_dwordx4 v[60:63], v[40:41], off offset:3072
	v_add_u32_e32 v16, s6, v16
	s_waitcnt vmcnt(3)
	v_mov_b32_e32 v46, v29
	s_waitcnt vmcnt(2)
	v_mov_b32_e32 v47, v33
	v_mov_b32_e32 v42, v28
	v_mov_b32_e32 v43, v32
	v_pk_mul_f32 v[46:47], v[46:47], v[46:47]
	v_mov_b32_e32 v36, v30
	v_mov_b32_e32 v37, v34
	v_pk_fma_f32 v[42:43], v[42:43], v[42:43], v[46:47]
	v_mov_b32_e32 v38, v31
	v_mov_b32_e32 v39, v35
	v_pk_fma_f32 v[36:37], v[36:37], v[36:37], v[42:43]
	s_nop 0
	v_pk_fma_f32 v[46:47], v[38:39], v[38:39], v[36:37]
	v_add_f32_e32 v17, v46, v47
	s_waitcnt vmcnt(1)
	v_mov_b32_e32 v54, v57
	s_waitcnt vmcnt(0)
	v_mov_b32_e32 v55, v61
	v_mov_b32_e32 v52, v56
	v_mov_b32_e32 v53, v60
	v_pk_mul_f32 v[54:55], v[54:55], v[54:55]
	v_mov_b32_e32 v48, v58
	v_mov_b32_e32 v49, v62
	v_pk_fma_f32 v[52:53], v[52:53], v[52:53], v[54:55]
	v_mov_b32_e32 v50, v59
	v_mov_b32_e32 v51, v63
	v_pk_fma_f32 v[48:49], v[48:49], v[48:49], v[52:53]
	s_nop 0
	v_pk_fma_f32 v[48:49], v[50:51], v[50:51], v[48:49]
	s_nop 0
	v_add_f32_e32 v17, v17, v48
	v_add_f32_e32 v17, v17, v49
	ds_bpermute_b32 v46, v22, v17
	s_waitcnt lgkmcnt(0)
	v_add_f32_e32 v17, v17, v46
	ds_bpermute_b32 v46, v23, v17
	s_waitcnt lgkmcnt(0)
	v_add_f32_e32 v17, v17, v46
	ds_bpermute_b32 v46, v24, v17
	s_waitcnt lgkmcnt(0)
	v_add_f32_e32 v17, v17, v46
	ds_bpermute_b32 v46, v25, v17
	s_waitcnt lgkmcnt(0)
	v_add_f32_e32 v17, v17, v46
	ds_bpermute_b32 v46, v26, v17
	s_waitcnt lgkmcnt(0)
	v_add_f32_e32 v17, v17, v46
	ds_bpermute_b32 v46, v27, v17
	s_waitcnt lgkmcnt(0)
	v_add_f32_e32 v17, v17, v46
	v_fmamk_f32 v17, v17, 0x3a800000, v187
	v_cmp_gt_f32_e32 vcc, s79, v17
	v_mul_f32_e32 v46, 0x4b800000, v17
	s_nop 0
	v_cndmask_b32_e32 v17, v17, v46, vcc
	v_rsq_f32_e32 v17, v17
	s_nop 0
	v_mul_f32_e32 v46, 0x45800000, v17
	v_cndmask_b32_e32 v46, v17, v46, vcc
	v_pk_mul_f32 v[28:29], v[28:29], v[46:47] op_sel_hi:[1,0]
	v_pk_mul_f32 v[30:31], v[30:31], v[46:47] op_sel_hi:[1,0]
	v_pk_mul_f32 v[28:29], v[0:1], v[28:29]
	v_pk_mul_f32 v[30:31], v[2:3], v[30:31]
	v_cvt_pk_bf16_f32 v28, v28, v29
	v_cvt_pk_bf16_f32 v29, v30, v31
	global_store_dwordx2 v[44:45], v[28:29], off
	v_pk_mul_f32 v[28:29], v[32:33], v[46:47] op_sel_hi:[1,0]
	v_pk_mul_f32 v[30:31], v[34:35], v[46:47] op_sel_hi:[1,0]
	v_pk_mul_f32 v[28:29], v[4:5], v[28:29]
	v_pk_mul_f32 v[30:31], v[6:7], v[30:31]
	v_cvt_pk_bf16_f32 v28, v28, v29
	v_cvt_pk_bf16_f32 v29, v30, v31
	global_store_dwordx2 v[44:45], v[28:29], off offset:512
	v_pk_mul_f32 v[28:29], v[56:57], v[46:47] op_sel_hi:[1,0]
	v_pk_mul_f32 v[30:31], v[58:59], v[46:47] op_sel_hi:[1,0]
	v_pk_mul_f32 v[28:29], v[8:9], v[28:29]
	v_pk_mul_f32 v[30:31], v[10:11], v[30:31]
	v_cvt_pk_bf16_f32 v28, v28, v29
	v_cvt_pk_bf16_f32 v29, v30, v31
	global_store_dwordx2 v[44:45], v[28:29], off offset:1024
	v_pk_mul_f32 v[28:29], v[60:61], v[46:47] op_sel_hi:[1,0]
	v_pk_mul_f32 v[30:31], v[62:63], v[46:47] op_sel_hi:[1,0]
	v_pk_mul_f32 v[28:29], v[12:13], v[28:29]
	v_pk_mul_f32 v[30:31], v[14:15], v[30:31]
	v_cmp_lt_i32_e32 vcc, s25, v16
	v_cvt_pk_bf16_f32 v28, v28, v29
	v_cvt_pk_bf16_f32 v29, v30, v31
	s_or_b64 s[0:1], vcc, s[0:1]
	global_store_dwordx2 v[44:45], v[28:29], off offset:1536
	s_andn2_b64 exec, exec, s[0:1]
	s_cbranch_execnz .LBB0_286

.Lp2_rope:
	v_mul_lo_u32 v66, v64, s14
	v_lshl_add_u32 v66, v65, 3, v66
	s_lshl_b32 s15, s14, 5
	v_add_u32_e32 v67, s15, v66
	v_lshlrev_b32_e32 v68, 7, v64
	v_lshl_add_u32 v68, v65, 4, v68
	v_add_u32_e32 v69, 0x1000, v68
	s_lshl_b32 s33, s6, 7
	s_add_u32 s34, s33, 0xda00000
	s_add_u32 s68, s88, s34
	s_addc_u32 s69, s89, 0
	s_add_u32 s34, s33, 0xdc00000
	s_add_u32 s70, s88, s34
	s_addc_u32 s71, s89, 0
	global_load_dwordx4 v[96:99], v68, s[68:69]
	global_load_dwordx4 v[112:115], v68, s[70:71]
	global_load_dwordx4 v[100:103], v68, s[68:69] offset:32
	global_load_dwordx4 v[116:119], v68, s[70:71] offset:32
	global_load_dwordx4 v[104:107], v68, s[68:69] offset:64
	global_load_dwordx4 v[120:123], v68, s[70:71] offset:64
	global_load_dwordx4 v[108:111], v68, s[68:69] offset:96
	global_load_dwordx4 v[124:127], v68, s[70:71] offset:96
	s_waitcnt vmcnt(6)
	v_mul_f32_e32 v70, v32, v112
	v_mul_f32_e32 v71, v33, v113
	v_mul_f32_e32 v72, v34, v114
	v_mul_f32_e32 v73, v35, v115
	v_mul_f32_e32 v74, v48, v112
	v_mul_f32_e32 v75, v49, v113
	v_mul_f32_e32 v76, v50, v114
	v_mul_f32_e32 v77, v51, v115
	v_fma_f32 v70, v48, v96, -v70
	v_fma_f32 v71, v49, v97, -v71
	v_fma_f32 v72, v50, v98, -v72
	v_fma_f32 v73, v51, v99, -v73
	v_fmac_f32_e32 v74, v32, v96
	v_fmac_f32_e32 v75, v33, v97
	v_fmac_f32_e32 v76, v34, v98
	v_fmac_f32_e32 v77, v35, v99
	v_cvt_pk_bf16_f32 v78, v70, v71
	v_cvt_pk_bf16_f32 v79, v72, v73
	v_cvt_pk_bf16_f32 v80, v74, v75
	v_cvt_pk_bf16_f32 v81, v76, v77
	global_store_dwordx2 v66, v[78:79], s[40:41]
	global_store_dwordx2 v66, v[80:81], s[40:41] offset:64
	s_waitcnt vmcnt(6)
	v_mul_f32_e32 v70, v36, v116
	v_mul_f32_e32 v71, v37, v117
	v_mul_f32_e32 v72, v38, v118
	v_mul_f32_e32 v73, v39, v119
	v_mul_f32_e32 v74, v52, v116
	v_mul_f32_e32 v75, v53, v117
	v_mul_f32_e32 v76, v54, v118
	v_mul_f32_e32 v77, v55, v119
	v_fma_f32 v70, v52, v100, -v70
	v_fma_f32 v71, v53, v101, -v71
	v_fma_f32 v72, v54, v102, -v72
	v_fma_f32 v73, v55, v103, -v73
	v_fmac_f32_e32 v74, v36, v100
	v_fmac_f32_e32 v75, v37, v101
	v_fmac_f32_e32 v76, v38, v102
	v_fmac_f32_e32 v77, v39, v103
	v_cvt_pk_bf16_f32 v82, v70, v71
	v_cvt_pk_bf16_f32 v83, v72, v73
	v_cvt_pk_bf16_f32 v84, v74, v75
	v_cvt_pk_bf16_f32 v85, v76, v77
	global_store_dwordx2 v66, v[82:83], s[40:41] offset:16
	global_store_dwordx2 v66, v[84:85], s[40:41] offset:80
	s_waitcnt vmcnt(6)
	v_mul_f32_e32 v70, v40, v120
	v_mul_f32_e32 v71, v41, v121
	v_mul_f32_e32 v72, v42, v122
	v_mul_f32_e32 v73, v43, v123
	v_mul_f32_e32 v74, v56, v120
	v_mul_f32_e32 v75, v57, v121
	v_mul_f32_e32 v76, v58, v122
	v_mul_f32_e32 v77, v59, v123
	v_fma_f32 v70, v56, v104, -v70
	v_fma_f32 v71, v57, v105, -v71
	v_fma_f32 v72, v58, v106, -v72
	v_fma_f32 v73, v59, v107, -v73
	v_fmac_f32_e32 v74, v40, v104
	v_fmac_f32_e32 v75, v41, v105
	v_fmac_f32_e32 v76, v42, v106
	v_fmac_f32_e32 v77, v43, v107
	v_cvt_pk_bf16_f32 v78, v70, v71
	v_cvt_pk_bf16_f32 v79, v72, v73
	v_cvt_pk_bf16_f32 v80, v74, v75
	v_cvt_pk_bf16_f32 v81, v76, v77
	global_store_dwordx2 v66, v[78:79], s[40:41] offset:32
	global_store_dwordx2 v66, v[80:81], s[40:41] offset:96
	s_waitcnt vmcnt(6)
	v_mul_f32_e32 v70, v44, v124
	v_mul_f32_e32 v71, v45, v125
	v_mul_f32_e32 v72, v46, v126
	v_mul_f32_e32 v73, v47, v127
	v_mul_f32_e32 v74, v60, v124
	v_mul_f32_e32 v75, v61, v125
	v_mul_f32_e32 v76, v62, v126
	v_mul_f32_e32 v77, v63, v127
	v_fma_f32 v70, v60, v108, -v70
	v_fma_f32 v71, v61, v109, -v71
	v_fma_f32 v72, v62, v110, -v72
	v_fma_f32 v73, v63, v111, -v73
	v_fmac_f32_e32 v74, v44, v108
	v_fmac_f32_e32 v75, v45, v109
	v_fmac_f32_e32 v76, v46, v110
	v_fmac_f32_e32 v77, v47, v111
	v_cvt_pk_bf16_f32 v82, v70, v71
	v_cvt_pk_bf16_f32 v83, v72, v73
	v_cvt_pk_bf16_f32 v84, v74, v75
	v_cvt_pk_bf16_f32 v85, v76, v77
	global_store_dwordx2 v66, v[82:83], s[40:41] offset:48
	global_store_dwordx2 v66, v[84:85], s[40:41] offset:112
	global_load_dwordx4 v[96:99], v69, s[68:69]
	global_load_dwordx4 v[112:115], v69, s[70:71]
	global_load_dwordx4 v[100:103], v69, s[68:69] offset:32
	global_load_dwordx4 v[116:119], v69, s[70:71] offset:32
	global_load_dwordx4 v[104:107], v69, s[68:69] offset:64
	global_load_dwordx4 v[120:123], v69, s[70:71] offset:64
	global_load_dwordx4 v[108:111], v69, s[68:69] offset:96
	global_load_dwordx4 v[124:127], v69, s[70:71] offset:96
	s_waitcnt vmcnt(6)
	v_mul_f32_e32 v70, v0, v112
	v_mul_f32_e32 v71, v1, v113
	v_mul_f32_e32 v72, v2, v114
	v_mul_f32_e32 v73, v3, v115
	v_mul_f32_e32 v74, v16, v112
	v_mul_f32_e32 v75, v17, v113
	v_mul_f32_e32 v76, v18, v114
	v_mul_f32_e32 v77, v19, v115
	v_fma_f32 v70, v16, v96, -v70
	v_fma_f32 v71, v17, v97, -v71
	v_fma_f32 v72, v18, v98, -v72
	v_fma_f32 v73, v19, v99, -v73
	v_fmac_f32_e32 v74, v0, v96
	v_fmac_f32_e32 v75, v1, v97
	v_fmac_f32_e32 v76, v2, v98
	v_fmac_f32_e32 v77, v3, v99
	v_cvt_pk_bf16_f32 v78, v70, v71
	v_cvt_pk_bf16_f32 v79, v72, v73
	v_cvt_pk_bf16_f32 v80, v74, v75
	v_cvt_pk_bf16_f32 v81, v76, v77
	global_store_dwordx2 v67, v[78:79], s[40:41]
	global_store_dwordx2 v67, v[80:81], s[40:41] offset:64
	s_waitcnt vmcnt(6)
	v_mul_f32_e32 v70, v4, v116
	v_mul_f32_e32 v71, v5, v117
	v_mul_f32_e32 v72, v6, v118
	v_mul_f32_e32 v73, v7, v119
	v_mul_f32_e32 v74, v20, v116
	v_mul_f32_e32 v75, v21, v117
	v_mul_f32_e32 v76, v22, v118
	v_mul_f32_e32 v77, v23, v119
	v_fma_f32 v70, v20, v100, -v70
	v_fma_f32 v71, v21, v101, -v71
	v_fma_f32 v72, v22, v102, -v72
	v_fma_f32 v73, v23, v103, -v73
	v_fmac_f32_e32 v74, v4, v100
	v_fmac_f32_e32 v75, v5, v101
	v_fmac_f32_e32 v76, v6, v102
	v_fmac_f32_e32 v77, v7, v103
	v_cvt_pk_bf16_f32 v82, v70, v71
	v_cvt_pk_bf16_f32 v83, v72, v73
	v_cvt_pk_bf16_f32 v84, v74, v75
	v_cvt_pk_bf16_f32 v85, v76, v77
	global_store_dwordx2 v67, v[82:83], s[40:41] offset:16
	global_store_dwordx2 v67, v[84:85], s[40:41] offset:80
	s_waitcnt vmcnt(6)
	v_mul_f32_e32 v70, v8, v120
	v_mul_f32_e32 v71, v9, v121
	v_mul_f32_e32 v72, v10, v122
	v_mul_f32_e32 v73, v11, v123
	v_mul_f32_e32 v74, v24, v120
	v_mul_f32_e32 v75, v25, v121
	v_mul_f32_e32 v76, v26, v122
	v_mul_f32_e32 v77, v27, v123
	v_fma_f32 v70, v24, v104, -v70
	v_fma_f32 v71, v25, v105, -v71
	v_fma_f32 v72, v26, v106, -v72
	v_fma_f32 v73, v27, v107, -v73
	v_fmac_f32_e32 v74, v8, v104
	v_fmac_f32_e32 v75, v9, v105
	v_fmac_f32_e32 v76, v10, v106
	v_fmac_f32_e32 v77, v11, v107
	v_cvt_pk_bf16_f32 v78, v70, v71
	v_cvt_pk_bf16_f32 v79, v72, v73
	v_cvt_pk_bf16_f32 v80, v74, v75
	v_cvt_pk_bf16_f32 v81, v76, v77
	global_store_dwordx2 v67, v[78:79], s[40:41] offset:32
	global_store_dwordx2 v67, v[80:81], s[40:41] offset:96
	s_waitcnt vmcnt(6)
	v_mul_f32_e32 v70, v12, v124
	v_mul_f32_e32 v71, v13, v125
	v_mul_f32_e32 v72, v14, v126
	v_mul_f32_e32 v73, v15, v127
	v_mul_f32_e32 v74, v28, v124
	v_mul_f32_e32 v75, v29, v125
	v_mul_f32_e32 v76, v30, v126
	v_mul_f32_e32 v77, v31, v127
	v_fma_f32 v70, v28, v108, -v70
	v_fma_f32 v71, v29, v109, -v71
	v_fma_f32 v72, v30, v110, -v72
	v_fma_f32 v73, v31, v111, -v73
	v_fmac_f32_e32 v74, v12, v108
	v_fmac_f32_e32 v75, v13, v109
	v_fmac_f32_e32 v76, v14, v110
	v_fmac_f32_e32 v77, v15, v111
	v_cvt_pk_bf16_f32 v82, v70, v71
	v_cvt_pk_bf16_f32 v83, v72, v73
	v_cvt_pk_bf16_f32 v84, v74, v75
	v_cvt_pk_bf16_f32 v85, v76, v77
	global_store_dwordx2 v67, v[82:83], s[40:41] offset:48
	global_store_dwordx2 v67, v[84:85], s[40:41] offset:112
	s_movk_i32 s34, 0x3fff
	s_branch .LBB0_341
.Lp2_plain:
	v_mul_lo_u32 v66, v64, s14
	v_lshl_add_u32 v66, v65, 3, v66
	s_lshl_b32 s15, s14, 5
	v_add_u32_e32 v67, s15, v66
	v_cvt_pk_bf16_f32 v78, v48, v49
	v_cvt_pk_bf16_f32 v79, v50, v51
	v_cvt_pk_bf16_f32 v80, v32, v33
	v_cvt_pk_bf16_f32 v81, v34, v35
	global_store_dwordx2 v66, v[78:79], s[40:41]
	global_store_dwordx2 v66, v[80:81], s[40:41] offset:64
	v_cvt_pk_bf16_f32 v82, v52, v53
	v_cvt_pk_bf16_f32 v83, v54, v55
	v_cvt_pk_bf16_f32 v84, v36, v37
	v_cvt_pk_bf16_f32 v85, v38, v39
	global_store_dwordx2 v66, v[82:83], s[40:41] offset:16
	global_store_dwordx2 v66, v[84:85], s[40:41] offset:80
	v_cvt_pk_bf16_f32 v78, v56, v57
	v_cvt_pk_bf16_f32 v79, v58, v59
	v_cvt_pk_bf16_f32 v80, v40, v41
	v_cvt_pk_bf16_f32 v81, v42, v43
	global_store_dwordx2 v66, v[78:79], s[40:41] offset:32
	global_store_dwordx2 v66, v[80:81], s[40:41] offset:96
	v_cvt_pk_bf16_f32 v82, v60, v61
	v_cvt_pk_bf16_f32 v83, v62, v63
	v_cvt_pk_bf16_f32 v84, v44, v45
	v_cvt_pk_bf16_f32 v85, v46, v47
	global_store_dwordx2 v66, v[82:83], s[40:41] offset:48
	global_store_dwordx2 v66, v[84:85], s[40:41] offset:112
	v_cvt_pk_bf16_f32 v78, v16, v17
	v_cvt_pk_bf16_f32 v79, v18, v19
	v_cvt_pk_bf16_f32 v80, v0, v1
	v_cvt_pk_bf16_f32 v81, v2, v3
	global_store_dwordx2 v67, v[78:79], s[40:41]
	global_store_dwordx2 v67, v[80:81], s[40:41] offset:64
	v_cvt_pk_bf16_f32 v82, v20, v21
	v_cvt_pk_bf16_f32 v83, v22, v23
	v_cvt_pk_bf16_f32 v84, v4, v5
	v_cvt_pk_bf16_f32 v85, v6, v7
	global_store_dwordx2 v67, v[82:83], s[40:41] offset:16
	global_store_dwordx2 v67, v[84:85], s[40:41] offset:80
	v_cvt_pk_bf16_f32 v78, v24, v25
	v_cvt_pk_bf16_f32 v79, v26, v27
	v_cvt_pk_bf16_f32 v80, v8, v9
	v_cvt_pk_bf16_f32 v81, v10, v11
	global_store_dwordx2 v67, v[78:79], s[40:41] offset:32
	global_store_dwordx2 v67, v[80:81], s[40:41] offset:96
	v_cvt_pk_bf16_f32 v82, v28, v29
	v_cvt_pk_bf16_f32 v83, v30, v31
	v_cvt_pk_bf16_f32 v84, v12, v13
	v_cvt_pk_bf16_f32 v85, v14, v15
	global_store_dwordx2 v67, v[82:83], s[40:41] offset:48
	global_store_dwordx2 v67, v[84:85], s[40:41] offset:112
	s_movk_i32 s34, 0x3fff
	s_branch .LBB0_341
.Lp2_trans_setup:
	s_lshl_b32 s34, s30, 1
	s_add_u32 s34, s34, s13
	s_lshl_b32 s34, s34, 20
	s_lshl_b32 s35, s31, 1
	s_add_u32 s34, s34, s35
	s_add_u32 s33, s33, s34
	s_add_u32 s40, s88, s33
	s_addc_u32 s41, s89, 0
	v_lshlrev_b32_e32 v66, 1, v64
	v_lshl_add_u32 v66, v65, 16, v66
	s_movk_i32 s14, 0x4000
	v_mov_b32_e32 v67, v66
	v_cvt_pk_bf16_f32 v70, v48, v48
	global_store_short v67, v70, s[40:41]
	v_add_u32_e32 v67, 0x4000, v67
	v_cvt_pk_bf16_f32 v71, v49, v49
	global_store_short v67, v71, s[40:41]
	v_add_u32_e32 v67, 0x4000, v67
	v_cvt_pk_bf16_f32 v72, v50, v50
	global_store_short v67, v72, s[40:41]
	v_add_u32_e32 v67, 0x4000, v67
	v_cvt_pk_bf16_f32 v73, v51, v51
	global_store_short v67, v73, s[40:41]
	v_add_u32_e32 v67, 0x14000, v67
	v_cvt_pk_bf16_f32 v70, v52, v52
	global_store_short v67, v70, s[40:41]
	v_add_u32_e32 v67, 0x4000, v67
	v_cvt_pk_bf16_f32 v71, v53, v53
	global_store_short v67, v71, s[40:41]
	v_add_u32_e32 v67, 0x4000, v67
	v_cvt_pk_bf16_f32 v72, v54, v54
	global_store_short v67, v72, s[40:41]
	v_add_u32_e32 v67, 0x4000, v67
	v_cvt_pk_bf16_f32 v73, v55, v55
	global_store_short v67, v73, s[40:41]
	v_add_u32_e32 v67, 0x14000, v67
	s_waitcnt vmcnt(24)
	v_cvt_pk_bf16_f32 v70, v56, v56
	global_store_short v67, v70, s[40:41]
	v_add_u32_e32 v67, 0x4000, v67
	v_cvt_pk_bf16_f32 v71, v57, v57
	global_store_short v67, v71, s[40:41]
	v_add_u32_e32 v67, 0x4000, v67
	v_cvt_pk_bf16_f32 v72, v58, v58
	global_store_short v67, v72, s[40:41]
	v_add_u32_e32 v67, 0x4000, v67
	v_cvt_pk_bf16_f32 v73, v59, v59
	global_store_short v67, v73, s[40:41]
	v_add_u32_e32 v67, 0x14000, v67
	v_cvt_pk_bf16_f32 v70, v60, v60
	global_store_short v67, v70, s[40:41]
	v_add_u32_e32 v67, 0x4000, v67
	v_cvt_pk_bf16_f32 v71, v61, v61
	global_store_short v67, v71, s[40:41]
	v_add_u32_e32 v67, 0x4000, v67
	v_cvt_pk_bf16_f32 v72, v62, v62
	global_store_short v67, v72, s[40:41]
	v_add_u32_e32 v67, 0x4000, v67
	v_cvt_pk_bf16_f32 v73, v63, v63
	global_store_short v67, v73, s[40:41]
	v_add_u32_e32 v67, 0x14000, v67
	s_waitcnt vmcnt(24)
	v_cvt_pk_bf16_f32 v70, v32, v32
	global_store_short v67, v70, s[40:41]
	v_add_u32_e32 v67, 0x4000, v67
	v_cvt_pk_bf16_f32 v71, v33, v33
	global_store_short v67, v71, s[40:41]
	v_add_u32_e32 v67, 0x4000, v67
	v_cvt_pk_bf16_f32 v72, v34, v34
	global_store_short v67, v72, s[40:41]
	v_add_u32_e32 v67, 0x4000, v67
	v_cvt_pk_bf16_f32 v73, v35, v35
	global_store_short v67, v73, s[40:41]
	v_add_u32_e32 v67, 0x14000, v67
	v_cvt_pk_bf16_f32 v70, v36, v36
	global_store_short v67, v70, s[40:41]
	v_add_u32_e32 v67, 0x4000, v67
	v_cvt_pk_bf16_f32 v71, v37, v37
	global_store_short v67, v71, s[40:41]
	v_add_u32_e32 v67, 0x4000, v67
	v_cvt_pk_bf16_f32 v72, v38, v38
	global_store_short v67, v72, s[40:41]
	v_add_u32_e32 v67, 0x4000, v67
	v_cvt_pk_bf16_f32 v73, v39, v39
	global_store_short v67, v73, s[40:41]
	v_add_u32_e32 v67, 0x14000, v67
	s_waitcnt vmcnt(24)
	v_cvt_pk_bf16_f32 v70, v40, v40
	global_store_short v67, v70, s[40:41]
	v_add_u32_e32 v67, 0x4000, v67
	v_cvt_pk_bf16_f32 v71, v41, v41
	global_store_short v67, v71, s[40:41]
	v_add_u32_e32 v67, 0x4000, v67
	v_cvt_pk_bf16_f32 v72, v42, v42
	global_store_short v67, v72, s[40:41]
	v_add_u32_e32 v67, 0x4000, v67
	v_cvt_pk_bf16_f32 v73, v43, v43
	global_store_short v67, v73, s[40:41]
	v_add_u32_e32 v67, 0x14000, v67
	v_cvt_pk_bf16_f32 v70, v44, v44
	global_store_short v67, v70, s[40:41]
	v_add_u32_e32 v67, 0x4000, v67
	v_cvt_pk_bf16_f32 v71, v45, v45
	global_store_short v67, v71, s[40:41]
	v_add_u32_e32 v67, 0x4000, v67
	v_cvt_pk_bf16_f32 v72, v46, v46
	global_store_short v67, v72, s[40:41]
	v_add_u32_e32 v67, 0x4000, v67
	v_cvt_pk_bf16_f32 v73, v47, v47
	global_store_short v67, v73, s[40:41]
	v_add_u32_e32 v67, 0x14000, v67
	s_waitcnt vmcnt(24)
	v_add_u32_e32 v67, 64, v66
	v_cvt_pk_bf16_f32 v70, v16, v16
	global_store_short v67, v70, s[40:41]
	v_add_u32_e32 v67, 0x4000, v67
	v_cvt_pk_bf16_f32 v71, v17, v17
	global_store_short v67, v71, s[40:41]
	v_add_u32_e32 v67, 0x4000, v67
	v_cvt_pk_bf16_f32 v72, v18, v18
	global_store_short v67, v72, s[40:41]
	v_add_u32_e32 v67, 0x4000, v67
	v_cvt_pk_bf16_f32 v73, v19, v19
	global_store_short v67, v73, s[40:41]
	v_add_u32_e32 v67, 0x14000, v67
	v_cvt_pk_bf16_f32 v70, v20, v20
	global_store_short v67, v70, s[40:41]
	v_add_u32_e32 v67, 0x4000, v67
	v_cvt_pk_bf16_f32 v71, v21, v21
	global_store_short v67, v71, s[40:41]
	v_add_u32_e32 v67, 0x4000, v67
	v_cvt_pk_bf16_f32 v72, v22, v22
	global_store_short v67, v72, s[40:41]
	v_add_u32_e32 v67, 0x4000, v67
	v_cvt_pk_bf16_f32 v73, v23, v23
	global_store_short v67, v73, s[40:41]
	v_add_u32_e32 v67, 0x14000, v67
	s_waitcnt vmcnt(24)
	v_cvt_pk_bf16_f32 v70, v24, v24
	global_store_short v67, v70, s[40:41]
	v_add_u32_e32 v67, 0x4000, v67
	v_cvt_pk_bf16_f32 v71, v25, v25
	global_store_short v67, v71, s[40:41]
	v_add_u32_e32 v67, 0x4000, v67
	v_cvt_pk_bf16_f32 v72, v26, v26
	global_store_short v67, v72, s[40:41]
	v_add_u32_e32 v67, 0x4000, v67
	v_cvt_pk_bf16_f32 v73, v27, v27
	global_store_short v67, v73, s[40:41]
	v_add_u32_e32 v67, 0x14000, v67
	v_cvt_pk_bf16_f32 v70, v28, v28
	global_store_short v67, v70, s[40:41]
	v_add_u32_e32 v67, 0x4000, v67
	v_cvt_pk_bf16_f32 v71, v29, v29
	global_store_short v67, v71, s[40:41]
	v_add_u32_e32 v67, 0x4000, v67
	v_cvt_pk_bf16_f32 v72, v30, v30
	global_store_short v67, v72, s[40:41]
	v_add_u32_e32 v67, 0x4000, v67
	v_cvt_pk_bf16_f32 v73, v31, v31
	global_store_short v67, v73, s[40:41]
	v_add_u32_e32 v67, 0x14000, v67
	s_waitcnt vmcnt(24)
	v_cvt_pk_bf16_f32 v70, v0, v0
	global_store_short v67, v70, s[40:41]
	v_add_u32_e32 v67, 0x4000, v67
	v_cvt_pk_bf16_f32 v71, v1, v1
	global_store_short v67, v71, s[40:41]
	v_add_u32_e32 v67, 0x4000, v67
	v_cvt_pk_bf16_f32 v72, v2, v2
	global_store_short v67, v72, s[40:41]
	v_add_u32_e32 v67, 0x4000, v67
	v_cvt_pk_bf16_f32 v73, v3, v3
	global_store_short v67, v73, s[40:41]
	v_add_u32_e32 v67, 0x14000, v67
	v_cvt_pk_bf16_f32 v70, v4, v4
	global_store_short v67, v70, s[40:41]
	v_add_u32_e32 v67, 0x4000, v67
	v_cvt_pk_bf16_f32 v71, v5, v5
	global_store_short v67, v71, s[40:41]
	v_add_u32_e32 v67, 0x4000, v67
	v_cvt_pk_bf16_f32 v72, v6, v6
	global_store_short v67, v72, s[40:41]
	v_add_u32_e32 v67, 0x4000, v67
	v_cvt_pk_bf16_f32 v73, v7, v7
	global_store_short v67, v73, s[40:41]
	v_add_u32_e32 v67, 0x14000, v67
	s_waitcnt vmcnt(24)
	v_cvt_pk_bf16_f32 v70, v8, v8
	global_store_short v67, v70, s[40:41]
	v_add_u32_e32 v67, 0x4000, v67
	v_cvt_pk_bf16_f32 v71, v9, v9
	global_store_short v67, v71, s[40:41]
	v_add_u32_e32 v67, 0x4000, v67
	v_cvt_pk_bf16_f32 v72, v10, v10
	global_store_short v67, v72, s[40:41]
	v_add_u32_e32 v67, 0x4000, v67
	v_cvt_pk_bf16_f32 v73, v11, v11
	global_store_short v67, v73, s[40:41]
	v_add_u32_e32 v67, 0x14000, v67
	v_cvt_pk_bf16_f32 v70, v12, v12
	global_store_short v67, v70, s[40:41]
	v_add_u32_e32 v67, 0x4000, v67
	v_cvt_pk_bf16_f32 v71, v13, v13
	global_store_short v67, v71, s[40:41]
	v_add_u32_e32 v67, 0x4000, v67
	v_cvt_pk_bf16_f32 v72, v14, v14
	global_store_short v67, v72, s[40:41]
	v_add_u32_e32 v67, 0x4000, v67
	v_cvt_pk_bf16_f32 v73, v15, v15
	global_store_short v67, v73, s[40:41]
	v_add_u32_e32 v67, 0x14000, v67
	s_waitcnt vmcnt(24)
	s_movk_i32 s34, 0x3fff
	s_branch .LBB0_341

.LBB0_2206:
	v_ashrrev_i32_e32 v17, 31, v16
	s_waitcnt vmcnt(20)
	v_lshlrev_b64 v[28:29], 12, v[16:17]
	s_waitcnt vmcnt(15)
	v_lshl_add_u64 v[40:41], v[18:19], 0, v[28:29]
	v_lshlrev_b64 v[28:29], 11, v[16:17]
	s_waitcnt vmcnt(14)
	v_lshl_add_u64 v[44:45], v[20:21], 0, v[28:29]
	global_load_dwordx4 v[28:31], v[40:41], off
	global_load_dwordx4 v[32:35], v[40:41], off offset:1024
	global_load_dwordx4 v[56:59], v[40:41], off offset:2048
	global_load_dwordx4 v[60:63], v[40:41], off offset:3072
	v_add_u32_e32 v16, s40, v16
	s_waitcnt vmcnt(3)
	v_mov_b32_e32 v46, v29
	s_waitcnt vmcnt(2)
	v_mov_b32_e32 v47, v33
	v_mov_b32_e32 v42, v28
	v_mov_b32_e32 v43, v32
	v_pk_mul_f32 v[46:47], v[46:47], v[46:47]
	v_mov_b32_e32 v36, v30
	v_mov_b32_e32 v37, v34
	v_pk_fma_f32 v[42:43], v[42:43], v[42:43], v[46:47]
	v_mov_b32_e32 v38, v31
	v_mov_b32_e32 v39, v35
	v_pk_fma_f32 v[36:37], v[36:37], v[36:37], v[42:43]
	s_nop 0
	v_pk_fma_f32 v[46:47], v[38:39], v[38:39], v[36:37]
	v_add_f32_e32 v17, v46, v47
	s_waitcnt vmcnt(1)
	v_mov_b32_e32 v54, v57
	s_waitcnt vmcnt(0)
	v_mov_b32_e32 v55, v61
	v_mov_b32_e32 v52, v56
	v_mov_b32_e32 v53, v60
	v_pk_mul_f32 v[54:55], v[54:55], v[54:55]
	v_mov_b32_e32 v48, v58
	v_mov_b32_e32 v49, v62
	v_pk_fma_f32 v[52:53], v[52:53], v[52:53], v[54:55]
	v_mov_b32_e32 v50, v59
	v_mov_b32_e32 v51, v63
	v_pk_fma_f32 v[48:49], v[48:49], v[48:49], v[52:53]
	s_nop 0
	v_pk_fma_f32 v[48:49], v[50:51], v[50:51], v[48:49]
	s_nop 0
	v_add_f32_e32 v17, v17, v48
	v_add_f32_e32 v17, v17, v49
	ds_bpermute_b32 v46, v22, v17
	s_waitcnt lgkmcnt(0)
	v_add_f32_e32 v17, v17, v46
	ds_bpermute_b32 v46, v23, v17
	s_waitcnt lgkmcnt(0)
	v_add_f32_e32 v17, v17, v46
	ds_bpermute_b32 v46, v24, v17
	s_waitcnt lgkmcnt(0)
	v_add_f32_e32 v17, v17, v46
	ds_bpermute_b32 v46, v25, v17
	s_waitcnt lgkmcnt(0)
	v_add_f32_e32 v17, v17, v46
	ds_bpermute_b32 v46, v26, v17
	s_waitcnt lgkmcnt(0)
	v_add_f32_e32 v17, v17, v46
	ds_bpermute_b32 v46, v27, v17
	s_waitcnt lgkmcnt(0)
	v_add_f32_e32 v17, v17, v46
	v_fmamk_f32 v17, v17, 0x3a800000, v187
	v_cmp_gt_f32_e32 vcc, s79, v17
	v_mul_f32_e32 v46, 0x4b800000, v17
	s_nop 0
	v_cndmask_b32_e32 v17, v17, v46, vcc
	v_rsq_f32_e32 v17, v17
	s_nop 0
	v_mul_f32_e32 v46, 0x45800000, v17
	v_cndmask_b32_e32 v46, v17, v46, vcc
	v_pk_mul_f32 v[28:29], v[28:29], v[46:47] op_sel_hi:[1,0]
	v_pk_mul_f32 v[30:31], v[30:31], v[46:47] op_sel_hi:[1,0]
	v_pk_mul_f32 v[28:29], v[0:1], v[28:29]
	v_pk_mul_f32 v[30:31], v[2:3], v[30:31]
	v_cvt_pk_bf16_f32 v28, v28, v29
	v_cvt_pk_bf16_f32 v29, v30, v31
	global_store_dwordx2 v[44:45], v[28:29], off
	v_pk_mul_f32 v[28:29], v[32:33], v[46:47] op_sel_hi:[1,0]
	v_pk_mul_f32 v[30:31], v[34:35], v[46:47] op_sel_hi:[1,0]
	v_pk_mul_f32 v[28:29], v[4:5], v[28:29]
	v_pk_mul_f32 v[30:31], v[6:7], v[30:31]
	v_cvt_pk_bf16_f32 v28, v28, v29
	v_cvt_pk_bf16_f32 v29, v30, v31
	global_store_dwordx2 v[44:45], v[28:29], off offset:512
	v_pk_mul_f32 v[28:29], v[56:57], v[46:47] op_sel_hi:[1,0]
	v_pk_mul_f32 v[30:31], v[58:59], v[46:47] op_sel_hi:[1,0]
	v_pk_mul_f32 v[28:29], v[8:9], v[28:29]
	v_pk_mul_f32 v[30:31], v[10:11], v[30:31]
	v_cvt_pk_bf16_f32 v28, v28, v29
	v_cvt_pk_bf16_f32 v29, v30, v31
	global_store_dwordx2 v[44:45], v[28:29], off offset:1024
	v_pk_mul_f32 v[28:29], v[60:61], v[46:47] op_sel_hi:[1,0]
	v_pk_mul_f32 v[30:31], v[62:63], v[46:47] op_sel_hi:[1,0]
	v_pk_mul_f32 v[28:29], v[12:13], v[28:29]
	v_pk_mul_f32 v[30:31], v[14:15], v[30:31]
	v_cmp_lt_i32_e32 vcc, s34, v16
	v_cvt_pk_bf16_f32 v28, v28, v29
	v_cvt_pk_bf16_f32 v29, v30, v31
	s_or_b64 s[4:5], vcc, s[4:5]
	global_store_dwordx2 v[44:45], v[28:29], off offset:1536
	s_andn2_b64 exec, exec, s[4:5]
	s_cbranch_execnz .LBB0_2206

.LBB0_2397:
	v_ashrrev_i32_e32 v17, 31, v16
	s_waitcnt vmcnt(20)
	v_lshlrev_b64 v[28:29], 12, v[16:17]
	s_waitcnt vmcnt(15)
	v_lshl_add_u64 v[40:41], v[18:19], 0, v[28:29]
	v_lshlrev_b64 v[28:29], 11, v[16:17]
	s_waitcnt vmcnt(14)
	v_lshl_add_u64 v[44:45], v[20:21], 0, v[28:29]
	global_load_dwordx4 v[28:31], v[40:41], off
	global_load_dwordx4 v[32:35], v[40:41], off offset:1024
	global_load_dwordx4 v[56:59], v[40:41], off offset:2048
	global_load_dwordx4 v[60:63], v[40:41], off offset:3072
	v_add_u32_e32 v16, s40, v16
	s_waitcnt vmcnt(3)
	v_mov_b32_e32 v46, v29
	s_waitcnt vmcnt(2)
	v_mov_b32_e32 v47, v33
	v_mov_b32_e32 v42, v28
	v_mov_b32_e32 v43, v32
	v_pk_mul_f32 v[46:47], v[46:47], v[46:47]
	v_mov_b32_e32 v36, v30
	v_mov_b32_e32 v37, v34
	v_pk_fma_f32 v[42:43], v[42:43], v[42:43], v[46:47]
	v_mov_b32_e32 v38, v31
	v_mov_b32_e32 v39, v35
	v_pk_fma_f32 v[36:37], v[36:37], v[36:37], v[42:43]
	s_nop 0
	v_pk_fma_f32 v[46:47], v[38:39], v[38:39], v[36:37]
	v_add_f32_e32 v17, v46, v47
	s_waitcnt vmcnt(1)
	v_mov_b32_e32 v54, v57
	s_waitcnt vmcnt(0)
	v_mov_b32_e32 v55, v61
	v_mov_b32_e32 v52, v56
	v_mov_b32_e32 v53, v60
	v_pk_mul_f32 v[54:55], v[54:55], v[54:55]
	v_mov_b32_e32 v48, v58
	v_mov_b32_e32 v49, v62
	v_pk_fma_f32 v[52:53], v[52:53], v[52:53], v[54:55]
	v_mov_b32_e32 v50, v59
	v_mov_b32_e32 v51, v63
	v_pk_fma_f32 v[48:49], v[48:49], v[48:49], v[52:53]
	s_nop 0
	v_pk_fma_f32 v[48:49], v[50:51], v[50:51], v[48:49]
	s_nop 0
	v_add_f32_e32 v17, v17, v48
	v_add_f32_e32 v17, v17, v49
	ds_bpermute_b32 v46, v22, v17
	s_waitcnt lgkmcnt(0)
	v_add_f32_e32 v17, v17, v46
	ds_bpermute_b32 v46, v23, v17
	s_waitcnt lgkmcnt(0)
	v_add_f32_e32 v17, v17, v46
	ds_bpermute_b32 v46, v24, v17
	s_waitcnt lgkmcnt(0)
	v_add_f32_e32 v17, v17, v46
	ds_bpermute_b32 v46, v25, v17
	s_waitcnt lgkmcnt(0)
	v_add_f32_e32 v17, v17, v46
	ds_bpermute_b32 v46, v26, v17
	s_waitcnt lgkmcnt(0)
	v_add_f32_e32 v17, v17, v46
	ds_bpermute_b32 v46, v27, v17
	s_waitcnt lgkmcnt(0)
	v_add_f32_e32 v17, v17, v46
	v_fmamk_f32 v17, v17, 0x3a800000, v187
	v_cmp_gt_f32_e32 vcc, s79, v17
	v_mul_f32_e32 v46, 0x4b800000, v17
	s_nop 0
	v_cndmask_b32_e32 v17, v17, v46, vcc
	v_rsq_f32_e32 v17, v17
	s_nop 0
	v_mul_f32_e32 v46, 0x45800000, v17
	v_cndmask_b32_e32 v46, v17, v46, vcc
	v_pk_mul_f32 v[28:29], v[28:29], v[46:47] op_sel_hi:[1,0]
	v_pk_mul_f32 v[30:31], v[30:31], v[46:47] op_sel_hi:[1,0]
	v_pk_mul_f32 v[28:29], v[0:1], v[28:29]
	v_pk_mul_f32 v[30:31], v[2:3], v[30:31]
	v_cvt_pk_bf16_f32 v28, v28, v29
	v_cvt_pk_bf16_f32 v29, v30, v31
	global_store_dwordx2 v[44:45], v[28:29], off
	v_pk_mul_f32 v[28:29], v[32:33], v[46:47] op_sel_hi:[1,0]
	v_pk_mul_f32 v[30:31], v[34:35], v[46:47] op_sel_hi:[1,0]
	v_pk_mul_f32 v[28:29], v[4:5], v[28:29]
	v_pk_mul_f32 v[30:31], v[6:7], v[30:31]
	v_cvt_pk_bf16_f32 v28, v28, v29
	v_cvt_pk_bf16_f32 v29, v30, v31
	global_store_dwordx2 v[44:45], v[28:29], off offset:512
	v_pk_mul_f32 v[28:29], v[56:57], v[46:47] op_sel_hi:[1,0]
	v_pk_mul_f32 v[30:31], v[58:59], v[46:47] op_sel_hi:[1,0]
	v_pk_mul_f32 v[28:29], v[8:9], v[28:29]
	v_pk_mul_f32 v[30:31], v[10:11], v[30:31]
	v_cvt_pk_bf16_f32 v28, v28, v29
	v_cvt_pk_bf16_f32 v29, v30, v31
	global_store_dwordx2 v[44:45], v[28:29], off offset:1024
	v_pk_mul_f32 v[28:29], v[60:61], v[46:47] op_sel_hi:[1,0]
	v_pk_mul_f32 v[30:31], v[62:63], v[46:47] op_sel_hi:[1,0]
	v_pk_mul_f32 v[28:29], v[12:13], v[28:29]
	v_pk_mul_f32 v[30:31], v[14:15], v[30:31]
	v_cmp_lt_i32_e32 vcc, s34, v16
	v_cvt_pk_bf16_f32 v28, v28, v29
	v_cvt_pk_bf16_f32 v29, v30, v31
	s_or_b64 s[2:3], vcc, s[2:3]
	global_store_dwordx2 v[44:45], v[28:29], off offset:1536
	s_andn2_b64 exec, exec, s[2:3]
	s_cbranch_execnz .LBB0_2397
